# v35 + FFN-in main loop LDS-DMA loads use SGPR-base + 32-bit VGPR offset addressing (removes 16 v_lshl_add_u64 per iteration from the load segments)
# speedup vs baseline: 1.0137x; 1.0137x over previous
; #define PG8_STAGE(bufoff, gbase, voff) do { _Pragma("unroll") for (int _i = 0; _i < 2; ++_i) \
;         __builtin_amdgcn_global_load_lds((const unsigned*)((const char*)(gbase) + (voff)[_i]), (LAS unsigned*)(lds + (bufoff) + ldsw + _i * 8192), 16, 0, 0); } while (0)
; #define PG8_LDA(dst, b, h) do { _Pragma("unroll") for (int m = 0; m < 4; ++m) _Pragma("unroll") for (int k = 0; k < 2; ++k) dst[m][k] = *(const LAS bf16x8*)(lds + PG8_SA(b, h) + aoff + m * 2048 + k * 1024); } while (0)
; #define PG8_LDB(dst, b, h) do { _Pragma("unroll") for (int n = 0; n < 2; ++n) _Pragma("unroll") for (int k = 0; k < 2; ++k) dst[n][k] = *(const LAS bf16x8*)(lds + PG8_SB(b, h) + boff + n * 2048 + k * 1024); } while (0)
; #define PG8_MMA(ai, bj, At, Bt) do { __builtin_amdgcn_s_setprio(1); _Pragma("unroll") for (int m = 0; m < 4; ++m) _Pragma("unroll") for (int n = 0; n < 2; ++n) _Pragma("unroll") for (int k = 0; k < 2; ++k) \
;         acc[ai][bj][m][n] = __builtin_amdgcn_mfma_f32_16x16x32_bf16(Bt[n][k], At[m][k], acc[ai][bj][m][n], 0, 0, 0); __builtin_amdgcn_s_setprio(0); } while (0)
; #define PG8_WAIT_V(n) asm volatile("s_waitcnt vmcnt(" #n ")" ::: "memory")
; #define PG8_WAIT_L(n) asm volatile("s_waitcnt lgkmcnt(" #n ")" ::: "memory")
; #define PG8_BAR __builtin_amdgcn_s_barrier()
; #define PG8_SCHED __builtin_amdgcn_sched_barrier(0)
; template <class Epi, class Sched>
; __device__ __forceinline__ void gemm_phase(LAS unsigned char* lds, const Gemm g, const Sched& S, const Epi& E) {
;     ...
;             PG8_LDB(B0, 0, 0); PG8_LDB(B1, 0, 1); PG8_SCHED; PG8_LDA(At, 0, 0); PG8_STAGE(PG8_SA(1, 1), a1 + hsA, voffA);
;             PG8_WAIT_V(8); PG8_WAIT_L(0); PG8_BAR; PG8_MMA(0, 0, At, B0); PG8_MMA(0, 1, At, B1); PG8_BAR; PG8_SCHED;
;             PG8_LDA(At, 0, 1); PG8_STAGE(PG8_SB(0, 0), b2, voffB); PG8_STAGE(PG8_SB(0, 1), b2 + hsB, voffB); PG8_STAGE(PG8_SA(0, 0), a2, voffA);
;             PG8_WAIT_V(8); PG8_WAIT_L(0); PG8_BAR; PG8_MMA(1, 0, At, B0); PG8_MMA(1, 1, At, B1); PG8_BAR; PG8_SCHED;
;             PG8_LDB(B0, 1, 0); PG8_LDB(B1, 1, 1); PG8_SCHED; PG8_LDA(At, 1, 0); PG8_STAGE(PG8_SA(0, 1), a2 + hsA, voffA);
;             PG8_WAIT_V(8); PG8_WAIT_L(0); PG8_BAR; PG8_MMA(0, 0, At, B0); PG8_MMA(0, 1, At, B1); PG8_BAR; PG8_SCHED;
.Lnp_222:
.LBB0_222:
	s_add_i32 s96, s9, 2
	s_add_u32 s20, s0, 0xfffc0080
	s_addc_u32 s21, s1, -1
	s_add_i32 s74, 0, 0x10000
	s_cmp_eq_u32 s82, s9
	s_cselect_b32 s85, s10, s21
	s_cselect_b32 s84, s43, s20
	s_cselect_b32 s39, s45, s8
	s_cselect_b32 s38, vcc_lo, vcc_hi
	s_add_i32 s9, 0, 0x14000
	v_add_u32_e32 v154, s74, v160
	v_add_u32_e32 v174, s9, v160
	ds_read_b128 v[142:145], v154
	ds_read_b128 v[146:149], v154 offset:1024
	ds_read_b128 v[150:153], v154 offset:2048
	ds_read_b128 v[154:157], v154 offset:3072
	ds_read_b128 v[162:165], v174
	ds_read_b128 v[166:169], v174 offset:1024
	ds_read_b128 v[170:173], v174 offset:2048
	ds_read_b128 v[174:177], v174 offset:3072
	s_add_i32 m0, s16, 0xc000
	ds_read_b128 v[178:181], v161
	ds_read_b128 v[182:185], v161 offset:1024
	ds_read_b128 v[186:189], v161 offset:2048
	ds_read_b128 v[208:211], v161 offset:3072
	ds_read_b128 v[212:215], v161 offset:4096
	ds_read_b128 v[216:219], v161 offset:5120
	ds_read_b128 v[220:223], v161 offset:6144
	ds_read_b128 v[224:227], v161 offset:7168
	global_load_lds_dwordx4 v138, s[0:1]
	s_add_i32 m0, s16, 0xe000
	s_nop 0
	global_load_lds_dwordx4 v140, s[0:1]
	s_waitcnt vmcnt(8)
	s_waitcnt lgkmcnt(0)
	s_barrier
	s_waitcnt lgkmcnt(0)
	v_mfma_f32_16x16x32_bf16 v[122:125], v[142:145], v[178:181], v[122:125]
	v_mfma_f32_16x16x32_bf16 v[114:117], v[150:153], v[178:181], v[114:117]
	v_mfma_f32_16x16x32_bf16 v[106:109], v[142:145], v[186:189], v[106:109]
	v_mfma_f32_16x16x32_bf16 v[98:101], v[150:153], v[186:189], v[98:101]
	v_mfma_f32_16x16x32_bf16 v[90:93], v[142:145], v[212:215], v[90:93]
	v_mfma_f32_16x16x32_bf16 v[82:85], v[150:153], v[212:215], v[82:85]
	v_mfma_f32_16x16x32_bf16 v[74:77], v[142:145], v[220:223], v[74:77]
	v_mfma_f32_16x16x32_bf16 v[66:69], v[150:153], v[220:223], v[66:69]
	v_mfma_f32_16x16x32_bf16 v[122:125], v[146:149], v[182:185], v[122:125]
	v_mfma_f32_16x16x32_bf16 v[114:117], v[154:157], v[182:185], v[114:117]
	v_mfma_f32_16x16x32_bf16 v[106:109], v[146:149], v[208:211], v[106:109]
	v_mfma_f32_16x16x32_bf16 v[98:101], v[154:157], v[208:211], v[98:101]
	v_mfma_f32_16x16x32_bf16 v[90:93], v[146:149], v[216:219], v[90:93]
	v_mfma_f32_16x16x32_bf16 v[82:85], v[154:157], v[216:219], v[82:85]
	v_mfma_f32_16x16x32_bf16 v[74:77], v[146:149], v[224:227], v[74:77]
	v_mfma_f32_16x16x32_bf16 v[66:69], v[154:157], v[224:227], v[66:69]
	v_mfma_f32_16x16x32_bf16 v[126:129], v[162:165], v[178:181], v[126:129]
	v_mfma_f32_16x16x32_bf16 v[118:121], v[170:173], v[178:181], v[118:121]
	v_mfma_f32_16x16x32_bf16 v[110:113], v[162:165], v[186:189], v[110:113]
	v_mfma_f32_16x16x32_bf16 v[102:105], v[170:173], v[186:189], v[102:105]
	v_mfma_f32_16x16x32_bf16 v[94:97], v[162:165], v[212:215], v[94:97]
	v_mfma_f32_16x16x32_bf16 v[86:89], v[170:173], v[212:215], v[86:89]
	v_mfma_f32_16x16x32_bf16 v[78:81], v[162:165], v[220:223], v[78:81]
	v_mfma_f32_16x16x32_bf16 v[70:73], v[170:173], v[220:223], v[70:73]
	v_mfma_f32_16x16x32_bf16 v[126:129], v[166:169], v[182:185], v[126:129]
	v_mfma_f32_16x16x32_bf16 v[118:121], v[174:177], v[182:185], v[118:121]
	v_mfma_f32_16x16x32_bf16 v[110:113], v[166:169], v[208:211], v[110:113]
	v_mfma_f32_16x16x32_bf16 v[102:105], v[174:177], v[208:211], v[102:105]
	v_mfma_f32_16x16x32_bf16 v[94:97], v[166:169], v[216:219], v[94:97]
	v_mfma_f32_16x16x32_bf16 v[86:89], v[174:177], v[216:219], v[86:89]
	v_mfma_f32_16x16x32_bf16 v[78:81], v[166:169], v[224:227], v[78:81]
	v_mfma_f32_16x16x32_bf16 v[70:73], v[174:177], v[224:227], v[70:73]
	s_barrier
	s_add_i32 s20, s74, s12
	s_mov_b32 m0, s20
	ds_read_b128 v[178:181], v161 offset:16384
	ds_read_b128 v[182:185], v161 offset:17408
	ds_read_b128 v[186:189], v161 offset:18432
	ds_read_b128 v[208:211], v161 offset:19456
	ds_read_b128 v[212:215], v161 offset:20480
	ds_read_b128 v[216:219], v161 offset:21504
	ds_read_b128 v[220:223], v161 offset:22528
	ds_read_b128 v[224:227], v161 offset:23552
	global_load_lds_dwordx4 v0, s[38:39]
	s_add_i32 m0, s20, 0x2000
	s_add_u32 s20, s38, 0x40000
	s_addc_u32 s21, s39, 0
	s_add_i32 s9, s9, s12
	global_load_lds_dwordx4 v130, s[38:39]
	s_mov_b32 m0, s9
	s_nop 0
	global_load_lds_dwordx4 v0, s[20:21]
	s_add_i32 m0, s9, 0x2000
	s_nop 0
	global_load_lds_dwordx4 v130, s[20:21]
	s_mov_b32 m0, s16
	s_nop 0
	global_load_lds_dwordx4 v134, s[84:85]
	s_mov_b32 m0, s30
	s_nop 0
	global_load_lds_dwordx4 v132, s[84:85]
	s_waitcnt vmcnt(8)
	s_waitcnt lgkmcnt(0)
	s_barrier
	s_waitcnt lgkmcnt(0)
	v_mfma_f32_16x16x32_bf16 v[58:61], v[142:145], v[178:181], v[58:61]
	v_mfma_f32_16x16x32_bf16 v[50:53], v[150:153], v[178:181], v[50:53]
	v_mfma_f32_16x16x32_bf16 v[42:45], v[142:145], v[186:189], v[42:45]
	v_mfma_f32_16x16x32_bf16 v[34:37], v[150:153], v[186:189], v[34:37]
	v_mfma_f32_16x16x32_bf16 v[26:29], v[142:145], v[212:215], v[26:29]
	v_mfma_f32_16x16x32_bf16 v[18:21], v[150:153], v[212:215], v[18:21]
	v_mfma_f32_16x16x32_bf16 v[10:13], v[142:145], v[220:223], v[10:13]
	v_mfma_f32_16x16x32_bf16 v[2:5], v[150:153], v[220:223], v[2:5]
	v_mfma_f32_16x16x32_bf16 v[58:61], v[146:149], v[182:185], v[58:61]
	v_mfma_f32_16x16x32_bf16 v[50:53], v[154:157], v[182:185], v[50:53]
	v_mfma_f32_16x16x32_bf16 v[42:45], v[146:149], v[208:211], v[42:45]
	v_mfma_f32_16x16x32_bf16 v[34:37], v[154:157], v[208:211], v[34:37]
	v_mfma_f32_16x16x32_bf16 v[26:29], v[146:149], v[216:219], v[26:29]
	v_mfma_f32_16x16x32_bf16 v[18:21], v[154:157], v[216:219], v[18:21]
	v_mfma_f32_16x16x32_bf16 v[10:13], v[146:149], v[224:227], v[10:13]
	v_mfma_f32_16x16x32_bf16 v[2:5], v[154:157], v[224:227], v[2:5]
	v_mfma_f32_16x16x32_bf16 v[62:65], v[162:165], v[178:181], v[62:65]
	v_mfma_f32_16x16x32_bf16 v[54:57], v[170:173], v[178:181], v[54:57]
	v_mfma_f32_16x16x32_bf16 v[46:49], v[162:165], v[186:189], v[46:49]
	v_mfma_f32_16x16x32_bf16 v[38:41], v[170:173], v[186:189], v[38:41]
	v_mfma_f32_16x16x32_bf16 v[30:33], v[162:165], v[212:215], v[30:33]
	v_mfma_f32_16x16x32_bf16 v[22:25], v[170:173], v[212:215], v[22:25]
	v_mfma_f32_16x16x32_bf16 v[14:17], v[162:165], v[220:223], v[14:17]
	v_mfma_f32_16x16x32_bf16 v[6:9], v[170:173], v[220:223], v[6:9]
	v_mfma_f32_16x16x32_bf16 v[62:65], v[166:169], v[182:185], v[62:65]
	v_mfma_f32_16x16x32_bf16 v[54:57], v[174:177], v[182:185], v[54:57]
	v_mfma_f32_16x16x32_bf16 v[46:49], v[166:169], v[208:211], v[46:49]
	v_mfma_f32_16x16x32_bf16 v[38:41], v[174:177], v[208:211], v[38:41]
	v_mfma_f32_16x16x32_bf16 v[30:33], v[166:169], v[216:219], v[30:33]
	v_mfma_f32_16x16x32_bf16 v[22:25], v[174:177], v[216:219], v[22:25]
	v_mfma_f32_16x16x32_bf16 v[14:17], v[166:169], v[224:227], v[14:17]
	v_mfma_f32_16x16x32_bf16 v[6:9], v[174:177], v[224:227], v[6:9]
	s_barrier
; #define PG8_STAGE(bufoff, gbase, voff) do { _Pragma("unroll") for (int _i = 0; _i < 2; ++_i) \
;         __builtin_amdgcn_global_load_lds((const unsigned*)((const char*)(gbase) + (voff)[_i]), (LAS unsigned*)(lds + (bufoff) + ldsw + _i * 8192), 16, 0, 0); } while (0)
; #define PG8_LDA(dst, b, h) do { _Pragma("unroll") for (int m = 0; m < 4; ++m) _Pragma("unroll") for (int k = 0; k < 2; ++k) dst[m][k] = *(const LAS bf16x8*)(lds + PG8_SA(b, h) + aoff + m * 2048 + k * 1024); } while (0)
; #define PG8_MMA(ai, bj, At, Bt) do { __builtin_amdgcn_s_setprio(1); _Pragma("unroll") for (int m = 0; m < 4; ++m) _Pragma("unroll") for (int n = 0; n < 2; ++n) _Pragma("unroll") for (int k = 0; k < 2; ++k) \
;         acc[ai][bj][m][n] = __builtin_amdgcn_mfma_f32_16x16x32_bf16(Bt[n][k], At[m][k], acc[ai][bj][m][n], 0, 0, 0); __builtin_amdgcn_s_setprio(0); } while (0)
; #define PG8_WAIT_V(n) asm volatile("s_waitcnt vmcnt(" #n ")" ::: "memory")
; #define PG8_WAIT_L(n) asm volatile("s_waitcnt lgkmcnt(" #n ")" ::: "memory")
; #define PG8_BAR __builtin_amdgcn_s_barrier()
; #define PG8_SCHED __builtin_amdgcn_sched_barrier(0)
; template <class Epi, class Sched>
; __device__ __forceinline__ void gemm_phase(LAS unsigned char* lds, const Gemm g, const Sched& S, const Epi& E) {
;     ...
;             PG8_LDA(At, 1, 1); PG8_STAGE(PG8_SB(1, 0), b3, voffB); PG8_STAGE(PG8_SB(1, 1), b3 + hsB, voffB); PG8_STAGE(PG8_SA(1, 0), a3, voffA);
;             PG8_WAIT_V(8); PG8_WAIT_L(0); PG8_BAR; PG8_MMA(1, 0, At, B0); PG8_MMA(1, 1, At, B1); PG8_BAR; PG8_SCHED;
;         }
	s_add_i32 s9, 0, 0x18000
	s_add_i32 s74, 0, 0x1c000
	v_add_u32_e32 v154, s9, v160
	v_add_u32_e32 v174, s74, v160
	ds_read_b128 v[142:145], v154
	ds_read_b128 v[146:149], v154 offset:1024
	ds_read_b128 v[150:153], v154 offset:2048
	ds_read_b128 v[154:157], v154 offset:3072
	ds_read_b128 v[162:165], v174
	ds_read_b128 v[166:169], v174 offset:1024
	ds_read_b128 v[170:173], v174 offset:2048
	ds_read_b128 v[174:177], v174 offset:3072
	s_add_u32 s20, s84, 0x40000
	s_addc_u32 s21, s85, 0
	s_mov_b32 m0, s52
	ds_read_b128 v[178:181], v161 offset:32768
	ds_read_b128 v[182:185], v161 offset:33792
	ds_read_b128 v[186:189], v161 offset:34816
	ds_read_b128 v[208:211], v161 offset:35840
	ds_read_b128 v[212:215], v161 offset:36864
	ds_read_b128 v[216:219], v161 offset:37888
	ds_read_b128 v[220:223], v161 offset:38912
	ds_read_b128 v[224:227], v161 offset:39936
	global_load_lds_dwordx4 v134, s[20:21]
	s_mov_b32 m0, s56
	s_nop 0
	global_load_lds_dwordx4 v132, s[20:21]
	s_waitcnt vmcnt(8)
	s_waitcnt lgkmcnt(0)
	s_barrier
	s_waitcnt lgkmcnt(0)
	v_mfma_f32_16x16x32_bf16 v[122:125], v[142:145], v[178:181], v[122:125]
	v_mfma_f32_16x16x32_bf16 v[114:117], v[150:153], v[178:181], v[114:117]
	v_mfma_f32_16x16x32_bf16 v[106:109], v[142:145], v[186:189], v[106:109]
	v_mfma_f32_16x16x32_bf16 v[98:101], v[150:153], v[186:189], v[98:101]
	v_mfma_f32_16x16x32_bf16 v[90:93], v[142:145], v[212:215], v[90:93]
	v_mfma_f32_16x16x32_bf16 v[82:85], v[150:153], v[212:215], v[82:85]
	v_mfma_f32_16x16x32_bf16 v[74:77], v[142:145], v[220:223], v[74:77]
	v_mfma_f32_16x16x32_bf16 v[66:69], v[150:153], v[220:223], v[66:69]
	v_mfma_f32_16x16x32_bf16 v[122:125], v[146:149], v[182:185], v[122:125]
	v_mfma_f32_16x16x32_bf16 v[114:117], v[154:157], v[182:185], v[114:117]
	v_mfma_f32_16x16x32_bf16 v[106:109], v[146:149], v[208:211], v[106:109]
	v_mfma_f32_16x16x32_bf16 v[98:101], v[154:157], v[208:211], v[98:101]
	v_mfma_f32_16x16x32_bf16 v[90:93], v[146:149], v[216:219], v[90:93]
	v_mfma_f32_16x16x32_bf16 v[82:85], v[154:157], v[216:219], v[82:85]
	v_mfma_f32_16x16x32_bf16 v[74:77], v[146:149], v[224:227], v[74:77]
	v_mfma_f32_16x16x32_bf16 v[66:69], v[154:157], v[224:227], v[66:69]
	v_mfma_f32_16x16x32_bf16 v[126:129], v[162:165], v[178:181], v[126:129]
	v_mfma_f32_16x16x32_bf16 v[118:121], v[170:173], v[178:181], v[118:121]
	v_mfma_f32_16x16x32_bf16 v[110:113], v[162:165], v[186:189], v[110:113]
	v_mfma_f32_16x16x32_bf16 v[102:105], v[170:173], v[186:189], v[102:105]
	v_mfma_f32_16x16x32_bf16 v[94:97], v[162:165], v[212:215], v[94:97]
	v_mfma_f32_16x16x32_bf16 v[86:89], v[170:173], v[212:215], v[86:89]
	v_mfma_f32_16x16x32_bf16 v[78:81], v[162:165], v[220:223], v[78:81]
	v_mfma_f32_16x16x32_bf16 v[70:73], v[170:173], v[220:223], v[70:73]
	v_mfma_f32_16x16x32_bf16 v[126:129], v[166:169], v[182:185], v[126:129]
	v_mfma_f32_16x16x32_bf16 v[118:121], v[174:177], v[182:185], v[118:121]
	v_mfma_f32_16x16x32_bf16 v[110:113], v[166:169], v[208:211], v[110:113]
	v_mfma_f32_16x16x32_bf16 v[102:105], v[174:177], v[208:211], v[102:105]
	v_mfma_f32_16x16x32_bf16 v[94:97], v[166:169], v[216:219], v[94:97]
	v_mfma_f32_16x16x32_bf16 v[86:89], v[174:177], v[216:219], v[86:89]
	v_mfma_f32_16x16x32_bf16 v[78:81], v[166:169], v[224:227], v[78:81]
	v_mfma_f32_16x16x32_bf16 v[70:73], v[174:177], v[224:227], v[70:73]
	s_barrier
	s_add_i32 s9, s9, s12
	s_mov_b32 m0, s9
	s_add_u32 s20, s38, 0x80
	s_addc_u32 s21, s39, 0
	ds_read_b128 v[178:181], v161 offset:49152
	ds_read_b128 v[182:185], v161 offset:50176
	ds_read_b128 v[186:189], v161 offset:51200
	ds_read_b128 v[208:211], v161 offset:52224
	ds_read_b128 v[212:215], v161 offset:53248
	ds_read_b128 v[216:219], v161 offset:54272
	ds_read_b128 v[220:223], v161 offset:55296
	ds_read_b128 v[224:227], v161 offset:56320
	global_load_lds_dwordx4 v0, s[20:21]
	s_add_i32 m0, s9, 0x2000
	s_add_i32 s9, s74, s12
	global_load_lds_dwordx4 v130, s[20:21]
	s_add_u32 s20, s20, 0x40000
	s_addc_u32 s21, s21, 0
	s_mov_b32 m0, s9
	s_nop 0
	global_load_lds_dwordx4 v0, s[20:21]
	s_add_i32 m0, s9, 0x2000
	s_nop 0
	global_load_lds_dwordx4 v130, s[20:21]
	s_add_u32 s20, s84, 0x80
	s_addc_u32 s21, s85, 0
	s_mov_b32 m0, s78
	s_nop 0
	global_load_lds_dwordx4 v134, s[20:21]
	s_mov_b32 m0, s80
	s_nop 0
	global_load_lds_dwordx4 v132, s[20:21]
	s_waitcnt vmcnt(8)
	s_waitcnt lgkmcnt(0)
	s_barrier
	s_waitcnt lgkmcnt(0)
	v_mfma_f32_16x16x32_bf16 v[58:61], v[142:145], v[178:181], v[58:61]
	v_mfma_f32_16x16x32_bf16 v[50:53], v[150:153], v[178:181], v[50:53]
	v_mfma_f32_16x16x32_bf16 v[42:45], v[142:145], v[186:189], v[42:45]
	v_mfma_f32_16x16x32_bf16 v[34:37], v[150:153], v[186:189], v[34:37]
	v_mfma_f32_16x16x32_bf16 v[26:29], v[142:145], v[212:215], v[26:29]
	v_mfma_f32_16x16x32_bf16 v[18:21], v[150:153], v[212:215], v[18:21]
	v_mfma_f32_16x16x32_bf16 v[10:13], v[142:145], v[220:223], v[10:13]
	v_mfma_f32_16x16x32_bf16 v[2:5], v[150:153], v[220:223], v[2:5]
	v_mfma_f32_16x16x32_bf16 v[58:61], v[146:149], v[182:185], v[58:61]
	v_mfma_f32_16x16x32_bf16 v[50:53], v[154:157], v[182:185], v[50:53]
	v_mfma_f32_16x16x32_bf16 v[42:45], v[146:149], v[208:211], v[42:45]
	v_mfma_f32_16x16x32_bf16 v[34:37], v[154:157], v[208:211], v[34:37]
	v_mfma_f32_16x16x32_bf16 v[26:29], v[146:149], v[216:219], v[26:29]
	v_mfma_f32_16x16x32_bf16 v[18:21], v[154:157], v[216:219], v[18:21]
	v_mfma_f32_16x16x32_bf16 v[10:13], v[146:149], v[224:227], v[10:13]
	v_mfma_f32_16x16x32_bf16 v[2:5], v[154:157], v[224:227], v[2:5]
	v_mfma_f32_16x16x32_bf16 v[62:65], v[162:165], v[178:181], v[62:65]
	v_mfma_f32_16x16x32_bf16 v[54:57], v[170:173], v[178:181], v[54:57]
	v_mfma_f32_16x16x32_bf16 v[46:49], v[162:165], v[186:189], v[46:49]
	v_mfma_f32_16x16x32_bf16 v[38:41], v[170:173], v[186:189], v[38:41]
	v_mfma_f32_16x16x32_bf16 v[30:33], v[162:165], v[212:215], v[30:33]
	v_mfma_f32_16x16x32_bf16 v[22:25], v[170:173], v[212:215], v[22:25]
	v_mfma_f32_16x16x32_bf16 v[14:17], v[162:165], v[220:223], v[14:17]
	v_mfma_f32_16x16x32_bf16 v[6:9], v[170:173], v[220:223], v[6:9]
	v_mfma_f32_16x16x32_bf16 v[62:65], v[166:169], v[182:185], v[62:65]
	v_mfma_f32_16x16x32_bf16 v[54:57], v[174:177], v[182:185], v[54:57]
	v_mfma_f32_16x16x32_bf16 v[46:49], v[166:169], v[208:211], v[46:49]
	v_mfma_f32_16x16x32_bf16 v[38:41], v[174:177], v[208:211], v[38:41]
	v_mfma_f32_16x16x32_bf16 v[30:33], v[166:169], v[216:219], v[30:33]
	v_mfma_f32_16x16x32_bf16 v[22:25], v[174:177], v[216:219], v[22:25]
	v_mfma_f32_16x16x32_bf16 v[14:17], v[166:169], v[224:227], v[14:17]
	v_mfma_f32_16x16x32_bf16 v[6:9], v[174:177], v[224:227], v[6:9]
	s_barrier
	s_add_u32 s0, s0, 0x100
	s_addc_u32 s1, s1, 0
	s_add_u32 vcc_hi, vcc_hi, 0x100
	s_addc_u32 s8, s8, 0
	s_cmp_ge_i32 s96, s57
	s_mov_b32 s9, s96
	s_cbranch_scc0 .LBB0_222
	s_setprio 0
	v_readlane_b32 s96, v250, 43
	s_mov_b64 s[74:75], s[22:23]
